# stackE + CDIL combine loop: wide loads issued before the LSE wait (reorder + temp renames)
# speedup vs baseline: 1.0099x; 1.0017x over previous
; __device__ __forceinline__ unsigned pk_bf16(float lo, float hi) { const f32x2 v = {lo, hi}; const bf16v2 b = __builtin_convertvector(v, bf16v2); return __builtin_bit_cast(unsigned, b); }
; __device__ __forceinline__ float bf_lo(unsigned u) { return __uint_as_float(u << 16); }
; __device__ __forceinline__ float bf_hi(unsigned u) { return __uint_as_float(u & 0xffff0000u); }
; __device__ __forceinline__ float silu_f(float v) { return v * __builtin_amdgcn_rcpf(1.0f + __builtin_amdgcn_exp2f(-LOG2E * v)); }
; __device__ __forceinline__ int tid_opaque() { int t = threadIdx.x; asm volatile("" : "+v"(t)); return t; }
; __device__ __forceinline__ void dil_combine_phase(const Params& p, int half) {
;     ...
;     for (int idx = blockIdx.x * 512 + tid_opaque(); idx < 16384 * 128; idx += nth) {
;         const int row = idx >> 7, e = (idx & 127) * 8, h = e >> 7;
;         const float l0 = LSE[(size_t)row * 8 + h], l1 = LSE[(size_t)(16384 + row) * 8 + h], l2 = LSE[(size_t)(32768 + row) * 8 + h];
;         const float mx = fmaxf(l0, fmaxf(l1, l2)); float w0 = __builtin_amdgcn_exp2f(l0 - mx), w1 = __builtin_amdgcn_exp2f(l1 - mx), w2 = __builtin_amdgcn_exp2f(l2 - mx);
;         const float inv = 1.0f / (w0 + w1 + w2); w0 *= inv; w1 *= inv; w2 *= inv;
;         const u32x4 a = *(const u32x4*)(OG + (size_t)row * DM + e), b = *(const u32x4*)(OG + (size_t)(16384 + row) * DM + e), c = *(const u32x4*)(OG + (size_t)(32768 + row) * DM + e);
;         const u32x4 z = *(const u32x4*)(PROJ + (size_t)row * 8192 + 7168 + e);
;         u32x4 o;
; #pragma unroll
;         for (int j = 0; j < 4; ++j) {
;             const float lo = (w0 * bf_lo(a[j]) + w1 * bf_lo(b[j]) + w2 * bf_lo(c[j])) * silu_f(bf_lo(z[j]));
;             const float hi = (w0 * bf_hi(a[j]) + w1 * bf_hi(b[j]) + w2 * bf_hi(c[j])) * silu_f(bf_hi(z[j]));
;             o[j] = pk_bf16(lo, hi);
;         }
;         *(u32x4*)(Y + (size_t)row * DM + e) = o;
.LBB0_68:
	v_ashrrev_i32_e32 v20, 7, v1
	v_ashrrev_i32_e32 v21, 31, v20
	v_lshlrev_b64 v[2:3], 5, v[20:21]
	v_lshrrev_b32_e32 v4, 5, v7
	v_lshl_add_u64 v[2:3], s[58:59], 0, v[2:3]
	v_and_b32_e32 v4, 28, v4
	v_mov_b32_e32 v5, v0
	v_add_u32_e32 v12, 0x4000, v20
	v_lshl_add_u64 v[2:3], v[2:3], 0, v[4:5]
	v_ashrrev_i32_e32 v13, 31, v12
	global_load_dword v6, v[2:3], off
	v_lshlrev_b64 v[2:3], 5, v[12:13]
	v_lshl_add_u64 v[2:3], s[58:59], 0, v[2:3]
	v_add_u32_e32 v16, 0x8000, v20
	v_lshl_add_u64 v[2:3], v[2:3], 0, v[4:5]
	v_ashrrev_i32_e32 v17, 31, v16
	global_load_dword v42, v[2:3], off
	v_lshlrev_b64 v[2:3], 5, v[16:17]
	v_lshl_add_u64 v[2:3], s[58:59], 0, v[2:3]
	v_lshl_add_u64 v[2:3], v[2:3], 0, v[4:5]
	global_load_dword v2, v[2:3], off
	v_and_b32_e32 v10, 0x3f8, v7
	v_lshlrev_b64 v[16:17], 11, v[16:17]
	s_mov_b32 s2, 0xd603000
	v_lshl_add_u64 v[16:17], s[90:91], 0, v[16:17]
	v_lshlrev_b64 v[12:13], 11, v[12:13]
	v_lshl_add_u64 v[12:13], s[90:91], 0, v[12:13]
	v_add_u32_e32 v1, s64, v1
	v_lshlrev_b64 v[36:37], 11, v[20:21]
	v_lshlrev_b64 v[20:21], 14, v[20:21]
	v_lshlrev_b32_e32 v38, 1, v10
	v_mov_b32_e32 v39, v0
	v_lshl_add_u64 v[20:21], s[68:69], 0, v[20:21]
	v_lshl_add_u64 v[20:21], v[20:21], 0, v[38:39]
	v_add_co_u32_e32 v20, vcc, s2, v20
	v_lshl_add_u64 v[8:9], s[90:91], 0, v[36:37]
	v_lshl_add_u64 v[16:17], v[16:17], 0, v[38:39]
	v_addc_co_u32_e32 v21, vcc, 0, v21, vcc
	v_lshl_add_u64 v[8:9], v[8:9], 0, v[38:39]
	global_load_dwordx4 v[16:19], v[16:17], off
	v_lshl_add_u64 v[12:13], v[12:13], 0, v[38:39]
	global_load_dwordx4 v[20:23], v[20:21], off offset:2048
	global_load_dwordx4 v[8:11], v[8:9], off
	global_load_dwordx4 v[12:15], v[12:13], off
	s_waitcnt vmcnt(4)
	v_max3_f32 v3, v6, v42, v2
	v_sub_f32_e32 v4, v6, v3
	v_exp_f32_e32 v25, v4
	v_sub_f32_e32 v4, v42, v3
	v_exp_f32_e32 v24, v4
	v_sub_f32_e32 v2, v2, v3
	v_exp_f32_e32 v2, v2
	v_add_f32_e32 v3, v25, v24
	v_add_f32_e32 v3, v2, v3
	v_div_scale_f32 v4, s[4:5], v3, v3, 1.0
	v_rcp_f32_e32 v5, v4
	s_nop 0
	v_fma_f32 v6, -v4, v5, 1.0
	v_fmac_f32_e32 v5, v6, v5
	v_div_scale_f32 v6, vcc, 1.0, v3, 1.0
	v_mul_f32_e32 v42, v6, v5
	v_fma_f32 v43, -v4, v42, v6
	v_fmac_f32_e32 v42, v43, v5
	v_fma_f32 v4, -v4, v42, v6
	v_div_fmas_f32 v4, v4, v5, v42
	v_div_fixup_f32 v26, v4, v3, 1.0
	v_mul_f32_e32 v6, v2, v26
	v_pk_mul_f32 v[24:25], v[24:25], v[26:27] op_sel_hi:[1,0]
	s_mov_b32 s2, 0x1fffff
	v_lshl_add_u64 v[2:3], s[40:41], 0, v[36:37]
	v_cmp_lt_i32_e32 vcc, s2, v1
	v_lshl_add_u64 v[2:3], v[2:3], 0, v[38:39]
	s_or_b64 s[42:43], vcc, s[42:43]
	s_waitcnt vmcnt(3)
	v_lshlrev_b32_e32 v34, 16, v16
	v_and_b32_e32 v35, 0xffff0000, v16
	s_waitcnt vmcnt(2)
	v_lshlrev_b32_e32 v26, 16, v20
	v_and_b32_e32 v27, 0xffff0000, v20
	v_mul_f32_e32 v20, 0xbfb8aa3b, v26
	s_waitcnt vmcnt(1)
	v_and_b32_e32 v31, 0xffff0000, v8
	v_lshlrev_b32_e32 v32, 16, v8
	v_mul_f32_e32 v8, 0xbfb8aa3b, v27
	v_exp_f32_e32 v20, v20
	v_exp_f32_e32 v8, v8
	s_waitcnt vmcnt(0)
	v_and_b32_e32 v33, 0xffff0000, v12
	v_lshlrev_b32_e32 v30, 16, v12
	v_add_f32_e32 v20, 1.0, v20
	v_add_f32_e32 v8, 1.0, v8
	v_rcp_f32_e32 v28, v20
	v_rcp_f32_e32 v29, v8
	v_lshlrev_b32_e32 v20, 16, v21
	v_and_b32_e32 v21, 0xffff0000, v21
	v_mul_f32_e32 v12, 0xbfb8aa3b, v20
	v_pk_mul_f32 v[26:27], v[28:29], v[26:27]
	v_pk_mul_f32 v[28:29], v[24:25], v[32:33] op_sel:[1,0] op_sel_hi:[0,1]
	v_pk_fma_f32 v[28:29], v[24:25], v[30:31], v[28:29]
	v_exp_f32_e32 v12, v12
	v_pk_fma_f32 v[28:29], v[6:7], v[34:35], v[28:29] op_sel_hi:[0,1,1]
	v_pk_mul_f32 v[26:27], v[28:29], v[26:27]
	v_lshlrev_b32_e32 v28, 16, v9
	v_cvt_pk_bf16_f32 v8, v26, v27
	v_and_b32_e32 v27, 0xffff0000, v9
	v_mul_f32_e32 v9, 0xbfb8aa3b, v21
	v_exp_f32_e32 v9, v9
	v_add_f32_e32 v12, 1.0, v12
	v_rcp_f32_e32 v12, v12
	v_lshlrev_b32_e32 v26, 16, v13
	v_add_f32_e32 v9, 1.0, v9
	v_and_b32_e32 v29, 0xffff0000, v13
	v_rcp_f32_e32 v13, v9
	v_lshlrev_b32_e32 v16, 16, v17
	v_and_b32_e32 v17, 0xffff0000, v17
	v_pk_mul_f32 v[12:13], v[12:13], v[20:21]
	v_pk_mul_f32 v[20:21], v[24:25], v[28:29] op_sel:[1,0] op_sel_hi:[0,1]
	v_pk_fma_f32 v[20:21], v[24:25], v[26:27], v[20:21]
	v_lshlrev_b32_e32 v26, 16, v10
	v_pk_fma_f32 v[16:17], v[6:7], v[16:17], v[20:21] op_sel_hi:[0,1,1]
	v_pk_mul_f32 v[12:13], v[16:17], v[12:13]
	v_and_b32_e32 v21, 0xffff0000, v10
	v_cvt_pk_bf16_f32 v9, v12, v13
	v_lshlrev_b32_e32 v12, 16, v22
	v_and_b32_e32 v13, 0xffff0000, v22
	v_mul_f32_e32 v16, 0xbfb8aa3b, v12
	v_mul_f32_e32 v10, 0xbfb8aa3b, v13
	v_exp_f32_e32 v16, v16
	v_exp_f32_e32 v10, v10
	v_and_b32_e32 v27, 0xffff0000, v14
	v_lshlrev_b32_e32 v20, 16, v14
	v_add_f32_e32 v16, 1.0, v16
	v_add_f32_e32 v10, 1.0, v10
	v_rcp_f32_e32 v16, v16
	v_rcp_f32_e32 v17, v10
	v_lshlrev_b32_e32 v28, 16, v18
	v_and_b32_e32 v29, 0xffff0000, v18
	v_lshlrev_b32_e32 v18, 16, v19
	v_pk_mul_f32 v[12:13], v[16:17], v[12:13]
	v_pk_mul_f32 v[16:17], v[24:25], v[26:27] op_sel:[1,0] op_sel_hi:[0,1]
	v_pk_fma_f32 v[16:17], v[24:25], v[20:21], v[16:17]
	v_lshlrev_b32_e32 v20, 16, v11
	v_pk_fma_f32 v[16:17], v[6:7], v[28:29], v[16:17] op_sel_hi:[0,1,1]
	v_and_b32_e32 v21, 0xffff0000, v15
	v_pk_mul_f32 v[12:13], v[16:17], v[12:13]
	v_lshlrev_b32_e32 v16, 16, v15
	v_and_b32_e32 v17, 0xffff0000, v11
	v_pk_mul_f32 v[20:21], v[24:25], v[20:21] op_sel:[1,0] op_sel_hi:[0,1]
	v_cvt_pk_bf16_f32 v10, v12, v13
	v_lshlrev_b32_e32 v12, 16, v23
	v_and_b32_e32 v13, 0xffff0000, v23
	v_pk_fma_f32 v[16:17], v[24:25], v[16:17], v[20:21]
	v_and_b32_e32 v19, 0xffff0000, v19
	v_mul_f32_e32 v14, 0xbfb8aa3b, v12
	v_pk_fma_f32 v[16:17], v[6:7], v[18:19], v[16:17] op_sel_hi:[0,1,1]
	v_mul_f32_e32 v6, 0xbfb8aa3b, v13
	v_exp_f32_e32 v14, v14
	v_exp_f32_e32 v6, v6
	v_add_u32_e32 v7, s73, v7
	v_add_f32_e32 v14, 1.0, v14
	v_add_f32_e32 v6, 1.0, v6
	v_rcp_f32_e32 v14, v14
	v_rcp_f32_e32 v15, v6
	s_nop 0
	v_pk_mul_f32 v[12:13], v[14:15], v[12:13]
	s_nop 0
	v_pk_mul_f32 v[12:13], v[16:17], v[12:13]
	s_nop 0
	v_cvt_pk_bf16_f32 v11, v12, v13
	global_store_dwordx4 v[2:3], v[8:11], off
	s_andn2_b64 exec, exec, s[42:43]
	s_cbranch_execnz .LBB0_68
